# MOD finalize of phase 1 (12 batch rows) spread over all workgroups instead of workgroups 0-11
# speedup vs baseline: 1.0624x; 1.0042x over previous
.LBB0_799:
	s_andn2_b64 vcc, exec, s[0:1]
	s_cbranch_vccnz .LBB0_825
	v_readlane_b32 s6, v255, 13
	v_readlane_b32 s44, v255, 5
	v_readlane_b32 s45, v255, 6
	s_waitcnt vmcnt(0) lgkmcnt(0)
	s_mov_b32 s68, s6
.Lfin_loop:
	s_mul_i32 s38, s68, 0xaab
	s_lshr_b32 s38, s38, 16
	s_mul_i32 s39, s38, 24
	s_sub_u32 s39, s68, s39
	s_lshl_b32 s39, s39, 11
	v_lshl_add_u32 v2, v166, 2, s39
	s_mul_i32 s40, s38, 0xc000
	s_add_u32 s42, s24, s40
	s_addc_u32 s43, s25, 0
	global_load_dword v5, v2, s[44:45]
	s_add_u32 s46, s42, 0x4a80000
	s_addc_u32 s47, s43, 0
	global_load_dword v24, v2, s[46:47]
	s_add_u32 s46, s46, 0x90000
	s_addc_u32 s47, s47, 0
	global_load_dword v10, v2, s[46:47]
	s_add_u32 s46, s46, 0x90000
	s_addc_u32 s47, s47, 0
	global_load_dword v11, v2, s[46:47]
	s_add_u32 s46, s46, 0x90000
	s_addc_u32 s47, s47, 0
	global_load_dword v12, v2, s[46:47]
	s_add_u32 s46, s46, 0x90000
	s_addc_u32 s47, s47, 0
	global_load_dword v13, v2, s[46:47]
	s_add_u32 s46, s46, 0x90000
	s_addc_u32 s47, s47, 0
	global_load_dword v14, v2, s[46:47]
	s_add_u32 s46, s46, 0x90000
	s_addc_u32 s47, s47, 0
	global_load_dword v15, v2, s[46:47]
	s_add_u32 s46, s46, 0x90000
	s_addc_u32 s47, s47, 0
	global_load_dword v16, v2, s[46:47]
	s_add_u32 s46, s42, 0x4f00000
	s_addc_u32 s47, s43, 0
	s_waitcnt vmcnt(7)
	v_add_f32_e32 v5, v5, v24
	s_waitcnt vmcnt(6)
	v_add_f32_e32 v5, v5, v10
	s_waitcnt vmcnt(5)
	v_add_f32_e32 v5, v5, v11
	s_waitcnt vmcnt(4)
	v_add_f32_e32 v5, v5, v12
	s_waitcnt vmcnt(3)
	v_add_f32_e32 v5, v5, v13
	s_waitcnt vmcnt(2)
	v_add_f32_e32 v5, v5, v14
	s_waitcnt vmcnt(1)
	v_add_f32_e32 v5, v5, v15
	s_waitcnt vmcnt(0)
	v_add_f32_e32 v5, v5, v16
	global_store_dword v2, v5, s[46:47]
	s_addk_i32 s68, 0x100
	s_cmpk_lt_i32 s68, 0x120
	s_cbranch_scc1 .Lfin_loop
